# P0 split into early/late pass; late weight conversion runs beside the S5 scan (half the WGs before P2/P3, half after)
# speedup vs baseline: 1.0145x; 1.0145x over previous
.LBB0_15:
	s_load_dwordx4 s[4:7], s[86:87], 0x120
	s_lshr_b32 s85, s88, 6
	s_mul_i32 s97, s85, s94
	v_writelane_b32 v255, s0, 7
	s_add_i32 s0, s97, s2
	s_lshl_b32 s50, s94, 3
	v_writelane_b32 v255, s0, 8
	s_waitcnt lgkmcnt(0)
	s_cmp_lt_i32 s4, 1
	v_and_b32_e32 v244, 63, v0
	v_writelane_b32 v255, s1, 9
	s_cselect_b64 s[0:1], -1, 0
	s_cmp_gt_i32 s5, 0
	s_cselect_b64 s[4:5], -1, 0
	s_and_b64 s[0:1], s[0:1], s[4:5]
	s_andn2_b64 vcc, exec, s[0:1]
	s_cbranch_vccnz .LBB0_193
	s_mov_b32 s99, 1
.Lp0_body:
	s_mov_b64 s[18:19], s[86:87]
	s_load_dwordx2 s[16:17], s[18:19], 0x118
	v_readlane_b32 s0, v255, 8
	s_cmp_gt_i32 s0, 0xb5ff
	v_readlane_b32 s1, v255, 9
	s_cbranch_scc1 .LBB0_185
	s_lshl_b32 s8, s85, 14
	v_and_b32_e32 v1, 7, v0
	v_lshrrev_b32_e32 v7, 3, v244
	s_add_i32 s3, s8, 0
	v_mul_u32_u24_e32 v4, 0x420, v1
	v_lshlrev_b32_e32 v9, 2, v7
	v_and_b32_e32 v32, 31, v0
	v_mov_b32_e32 v5, 0
	v_add3_u32 v9, s3, v4, v9
	v_lshlrev_b32_e32 v4, 4, v1
	v_lshlrev_b32_e32 v34, 2, v32
	s_waitcnt lgkmcnt(0)
	v_lshl_add_u64 v[28:29], s[16:17], 0, v[4:5]
	s_mov_b64 s[6:7], 0x6700000
	v_mov_b32_e32 v35, v5
	v_lshl_add_u64 v[10:11], v[28:29], 0, s[6:7]
	v_lshl_add_u64 v[24:25], s[16:17], 0, v[34:35]
	s_mov_b64 s[6:7], 0x195000
	v_lshl_add_u64 v[12:13], v[24:25], 0, s[6:7]
	s_mov_b64 s[6:7], 0x198000
	v_lshl_add_u64 v[14:15], v[24:25], 0, s[6:7]
	s_mov_b64 s[6:7], 0x5b00000
	v_lshl_add_u64 v[16:17], v[28:29], 0, s[6:7]
	s_mov_b64 s[6:7], 0x194800
	v_lshl_add_u64 v[18:19], v[24:25], 0, s[6:7]
	s_mov_b64 s[6:7], 0x197800
	v_lshl_add_u64 v[20:21], v[24:25], 0, s[6:7]
	s_mov_b64 s[6:7], 0x194000
	v_lshl_add_u64 v[22:23], v[24:25], 0, s[6:7]
	s_mov_b64 s[6:7], 0x197000
	v_lshl_add_u64 v[24:25], v[24:25], 0, s[6:7]
	s_mov_b64 s[6:7], 0xa00000
	v_bfe_u32 v4, v0, 5, 1
	v_lshl_add_u64 v[26:27], v[28:29], 0, s[6:7]
	s_mov_b64 s[6:7], 0x200000
	v_lshlrev_b32_e32 v30, 7, v4
	v_mul_u32_u24_e32 v4, 0x1080, v4
	s_add_u32 s0, s16, 0x180000
	v_lshl_add_u64 v[28:29], v[28:29], 0, s[6:7]
	v_readlane_b32 s6, v255, 8
	v_or3_b32 v4, s8, v4, v34
	s_addc_u32 s1, s17, 0
	v_lshrrev_b32_e32 v2, 5, v244
	v_add_u32_e32 v6, s3, v34
	s_mov_b32 s10, s6
	s_add_i32 s3, s6, 0x9b00
	v_add_u32_e32 v47, 0, v4
	s_add_i32 s30, s6, 0xec00
	s_lshl_b32 s6, s6, 2
	v_mbcnt_lo_u32_b32 v4, -1, 0
	s_mov_b32 s21, 0
	v_and_b32_e32 v3, 32, v0
	v_cmp_gt_u32_e64 s[4:5], 32, v244
	v_lshlrev_b32_e32 v8, 3, v1
	v_or_b32_e32 v44, 8, v7
	v_or_b32_e32 v45, 16, v7
	v_or_b32_e32 v46, 24, v7
	v_mov_b32_e32 v1, v2
	v_mov_b32_e32 v31, v5
	s_add_i32 s31, s6, 0x3b800
	s_lshl_b32 s33, s94, 5
	s_add_i32 s36, s6, 0x3c000
	s_movk_i32 s37, 0x84
	s_movk_i32 s38, 0x7fff
	s_mov_b32 s39, 0xffff0000
	s_mov_b32 s40, 0x10000
	s_mov_b32 s41, 0x5300000
	s_mov_b32 s42, 0x5200000
	s_mov_b32 s43, 0x3200000
	s_mov_b32 s44, 0x1200000
	v_lshlrev_b32_e32 v32, 2, v32
	v_mbcnt_hi_u32_b32 v48, -1, v4
	s_mov_b32 s45, s10
	v_readlane_b32 s7, v255, 9
	s_branch .LBB0_19

.LBB0_19:
	s_cmpk_lt_u32 s45, 0x800
	s_cselect_b32 s98, 1, 0
	s_sub_u32 s100, s45, 0x6400
	s_cmpk_lt_u32 s100, 0x100
	s_cselect_b32 s98, 1, s98
	s_sub_u32 s100, s45, 0xad00
	s_cmpk_lt_u32 s100, 0x100
	s_cselect_b32 s98, 1, s98
	s_cmp_lg_u32 s98, s99
	s_cbranch_scc1 .LBB0_18
	s_cmpk_gt_i32 s45, 0x7ff
	s_mov_b64 s[6:7], -1
	s_cbranch_scc0 .LBB0_181
	s_cmpk_gt_u32 s45, 0xfff
	s_cbranch_scc0 .LBB0_176
	s_waitcnt lgkmcnt(0)
	s_load_dwordx4 s[8:11], s[18:19], 0x100
	s_cmpk_gt_u32 s45, 0x11ff
	s_cbranch_scc0 .LBB0_149
	s_cmpk_gt_u32 s45, 0x13ff
	s_cbranch_scc0 .LBB0_122
	s_cmpk_gt_u32 s45, 0x1bff
	s_cbranch_scc0 .LBB0_95
	s_add_i32 s46, s45, 0xffffe400
	s_cmpk_gt_u32 s46, 0x7ff
	s_cbranch_scc0 .LBB0_90
	s_add_i32 s28, s45, 0xffffdc00
	s_cmpk_gt_u32 s28, 0x48ff
	s_cselect_b64 s[22:23], -1, 0
	s_and_b64 s[6:7], s[22:23], exec
	s_cselect_b32 s20, 0xffffb700, 0
	s_add_i32 s29, s20, s28
	s_cmpk_gt_i32 s29, 0x1fff
	s_mov_b64 s[6:7], -1
	s_cbranch_scc0 .LBB0_63
	s_cmpk_gt_u32 s29, 0x3fff
	s_cbranch_scc0 .LBB0_58
	s_cmpk_gt_u32 s29, 0x40ff
	s_cbranch_scc0 .LBB0_53
	s_load_dwordx4 s[12:15], s[18:19], 0xe0
	s_load_dwordx2 s[24:25], s[18:19], 0xf8
	s_and_b64 s[26:27], s[22:23], exec
	s_cselect_b32 s49, 0x800, 0
	s_lshl_b32 s7, s49, 13
	v_mov_b32_e32 v33, v5
	s_waitcnt lgkmcnt(0)
	s_add_u32 s7, s24, s7
	s_addc_u32 s25, s25, 0
	s_add_i32 s24, s29, 0xbf00
	s_and_b32 s48, s24, 0xffc0
	s_lshl_b32 s24, s45, 5
	s_and_b32 s47, s24, 0x7e0
	s_lshl_b32 s24, s47, 2
	s_add_u32 s24, s7, s24
	s_addc_u32 s25, s25, 0
	s_mov_b32 s6, 0
	v_lshl_add_u64 v[34:35], s[24:25], 0, v[32:33]
	s_mov_b32 s7, s48
	s_mov_b32 s24, 1
	s_mov_b32 s25, 32

.LBB0_185:
	s_cmp_eq_u32 s99, 0
	s_cbranch_scc1 .Lp0_skip_p
	v_lshl_or_b32 v1, s2, 9, v0
	s_mov_b32 s0, 0x120000
	v_cmp_gt_i32_e32 vcc, s0, v1
	s_waitcnt lgkmcnt(0)
	s_and_saveexec_b64 s[8:9], vcc
	s_cbranch_execz .LBB0_192
	s_load_dwordx4 s[4:7], s[18:19], 0x10
	s_add_u32 s10, s16, 0xb800000
	s_addc_u32 s11, s17, 0
	s_lshl_b32 s0, s94, 9
	s_mov_b64 s[12:13], 0
	s_mov_b32 s1, 0x38e38e39
	s_mov_b32 s3, 0x90000
	s_mov_b32 s16, 0x7ffff
	v_mov_b32_e32 v3, 0
	s_movk_i32 s17, 0x7fff
	s_mov_b32 s18, 0xffff0000
	s_movk_i32 s19, 0x2400
	s_mov_b32 s20, 0x11ffff
	s_branch .LBB0_188

.Lp0_skip_p:
	s_waitcnt lgkmcnt(0)
	s_barrier
	s_cmp_eq_u32 s99, 1
	s_cbranch_scc1 .LBB0_193
	s_bitcmp1_b32 s2, 3
	s_cbranch_scc1 .Lp3_ret
	s_branch .Lp2_body

.LBB0_253:
	s_cmp_lt_i32 s8, 3
	s_cselect_b64 s[0:1], -1, 0
	s_cmp_gt_i32 s9, 2
	s_cselect_b64 s[4:5], -1, 0
	s_and_b64 s[0:1], s[0:1], s[4:5]
	s_andn2_b64 vcc, exec, s[0:1]
	s_cbranch_vccnz .LBB0_284
	s_bitcmp1_b32 s2, 3
	s_cbranch_scc1 .Lp2_body
	s_mov_b32 s99, 0
	s_branch .Lp0_body
.Lp2_body:
	s_mov_b64 s[36:37], s[86:87]
	s_load_dwordx16 s[4:19], s[36:37], 0x48
	s_and_b32 s33, s2, 0x7f
	s_lshl_b32 s0, s33, 2
	v_mov_b32_e32 v2, s0
	v_lshlrev_b32_e32 v1, 2, v244
	s_waitcnt lgkmcnt(0)
	global_load_dword v19, v2, s[8:9]
	v_lshl_or_b32 v1, s33, 8, v1
	global_load_dword v4, v1, s[6:7]
	global_load_dword v18, v1, s[4:5]
	s_mov_b32 s0, 0x652b82fe
	s_mov_b32 s1, 0x3ff71547
	s_mov_b32 s4, 0xfefa39ef
	s_mov_b32 s5, 0xbfe62e42
	s_mov_b32 s6, 0x3b39803f
	s_mov_b32 s7, 0xbc7abc9e
	s_mov_b32 s8, 0x6a5dcb37
	v_mov_b32_e32 v2, 0xfca7ab0c
	v_mov_b32_e32 v3, 0x3e928af3
	s_mov_b32 s9, 0x3e5ade15
	v_mov_b32_e32 v6, 0x623fde64
	v_mov_b32_e32 v7, 0x3ec71dee
	v_mov_b32_e32 v8, 0x7c89e6b0
	v_mov_b32_e32 v9, 0x3efa0199
	v_mov_b32_e32 v10, 0x14761f6e
	v_mov_b32_e32 v11, 0x3f2a01a0
	v_mov_b32_e32 v12, 0x1852b7b0
	v_mov_b32_e32 v13, 0x3f56c16c
	v_mov_b32_e32 v14, 0x11122322
	v_mov_b32_e32 v15, 0x3f811111
	v_mov_b32_e32 v16, 0x555502a1
	v_mov_b32_e32 v17, 0x3fa55555
	v_mov_b32_e32 v20, 0x55555511
	v_mov_b32_e32 v21, 0x3fc55555
	v_mov_b32_e32 v22, 11
	v_mov_b32_e32 v23, 0x3fe00000
	s_mov_b32 s3, 0x44800000
	s_mov_b32 s20, 0xc4866000
	v_mov_b32_e32 v1, 0x7ff00000
	s_waitcnt vmcnt(2)
	v_cvt_f64_f32_e32 v[24:25], v19
	v_mul_f64 v[26:27], v[24:25], s[0:1]
	v_rndne_f64_e32 v[26:27], v[26:27]
	v_fmac_f64_e32 v[24:25], s[4:5], v[26:27]
	v_fmac_f64_e32 v[24:25], s[6:7], v[26:27]
	v_fmac_f64_e32 v[2:3], s[8:9], v[24:25]
	v_fmac_f64_e32 v[6:7], v[24:25], v[2:3]
	v_fmac_f64_e32 v[8:9], v[24:25], v[6:7]
	v_fmac_f64_e32 v[10:11], v[24:25], v[8:9]
	v_fmac_f64_e32 v[12:13], v[24:25], v[10:11]
	v_fmac_f64_e32 v[14:15], v[24:25], v[12:13]
	v_fmac_f64_e32 v[16:17], v[24:25], v[14:15]
	v_fmac_f64_e32 v[20:21], v[24:25], v[16:17]
	v_fmac_f64_e32 v[22:23], v[24:25], v[20:21]
	v_fma_f64 v[2:3], v[24:25], v[22:23], 1.0
	v_cvt_i32_f64_e32 v28, v[26:27]
	v_fma_f64 v[2:3], v[24:25], v[2:3], 1.0
	v_ldexp_f64 v[2:3], v[2:3], v28
	v_cmp_nlt_f32_e32 vcc, s3, v19
	v_cmp_ngt_f32_e64 s[4:5], s20, v19
	s_waitcnt vmcnt(1)
	v_cvt_f64_f32_e32 v[4:5], v4
	v_cndmask_b32_e32 v1, v1, v3, vcc
	s_and_b64 vcc, s[4:5], vcc
	v_cndmask_b32_e64 v17, 0, v1, s[4:5]
	v_cndmask_b32_e32 v16, 0, v2, vcc
	s_mov_b32 s0, 0
	v_mul_f64 v[6:7], v[16:17], v[4:5]
	s_mov_b32 s1, 0x41d00000
	v_cmp_nlt_f64_e64 s[0:1], |v[6:7]|, s[0:1]
	s_and_saveexec_b64 s[4:5], s[0:1]
	s_xor_b64 s[6:7], exec, s[4:5]
	s_cbranch_execz .LBB0_256
	s_mov_b32 s0, 0
	s_mov_b32 s1, 0x7b000000
	s_movk_i32 s3, 0xff80
	v_and_b32_e32 v1, 0x7fffffff, v7
	v_ldexp_f64 v[10:11], |v[6:7]|, s3
	v_cmp_ge_f64_e64 vcc, |v[6:7]|, s[0:1]
	v_trig_preop_f64 v[2:3], |v[6:7]|, 0
	v_trig_preop_f64 v[8:9], |v[6:7]|, 1
	v_cndmask_b32_e32 v11, v1, v11, vcc
	v_cndmask_b32_e32 v10, v6, v10, vcc
	v_mul_f64 v[14:15], v[2:3], v[10:11]
	v_mul_f64 v[12:13], v[8:9], v[10:11]
	v_fma_f64 v[2:3], v[2:3], v[10:11], -v[14:15]
	v_add_f64 v[20:21], v[12:13], v[2:3]
	v_add_f64 v[28:29], v[20:21], -v[12:13]
	v_add_f64 v[2:3], v[2:3], -v[28:29]
	v_add_f64 v[28:29], v[20:21], -v[28:29]
	v_add_f64 v[28:29], v[12:13], -v[28:29]
	v_fma_f64 v[8:9], v[8:9], v[10:11], -v[12:13]
	v_trig_preop_f64 v[12:13], |v[6:7]|, 2
	v_add_f64 v[2:3], v[2:3], v[28:29]
	v_mul_f64 v[28:29], v[12:13], v[10:11]
	v_add_f64 v[30:31], v[28:29], v[8:9]
	v_add_f64 v[22:23], v[14:15], v[20:21]
	v_add_f64 v[32:33], v[30:31], v[2:3]
	v_ldexp_f64 v[24:25], v[22:23], -2
	v_add_f64 v[14:15], v[22:23], -v[14:15]
	v_add_f64 v[22:23], v[32:33], -v[30:31]
	v_add_f64 v[2:3], v[2:3], -v[22:23]
	v_add_f64 v[22:23], v[32:33], -v[22:23]
	v_add_f64 v[22:23], v[30:31], -v[22:23]
	v_add_f64 v[2:3], v[2:3], v[22:23]
	v_add_f64 v[22:23], v[30:31], -v[28:29]
	v_add_f64 v[8:9], v[8:9], -v[22:23]
	v_add_f64 v[22:23], v[30:31], -v[22:23]
	v_add_f64 v[22:23], v[28:29], -v[22:23]
	v_add_f64 v[8:9], v[8:9], v[22:23]
	s_mov_b32 s0, 0
	v_fract_f64_e32 v[26:27], v[24:25]
	v_add_f64 v[2:3], v[8:9], v[2:3]
	v_fma_f64 v[8:9], v[12:13], v[10:11], -v[28:29]
	s_mov_b32 s1, 0x7ff00000
	v_add_f64 v[14:15], v[20:21], -v[14:15]
	v_add_f64 v[2:3], v[8:9], v[2:3]
	v_ldexp_f64 v[8:9], v[26:27], 2
	v_cmp_neq_f64_e64 vcc, |v[24:25]|, s[0:1]
	v_add_f64 v[20:21], v[14:15], v[32:33]
	v_mov_b32_e32 v1, 0x40100000
	v_cndmask_b32_e32 v9, 0, v9, vcc
	v_cndmask_b32_e32 v8, 0, v8, vcc
	v_add_f64 v[10:11], v[20:21], v[8:9]
	v_cmp_gt_f64_e32 vcc, 0, v[10:11]
	v_mov_b32_e32 v10, 0
	v_add_f64 v[14:15], v[20:21], -v[14:15]
	v_cndmask_b32_e32 v11, 0, v1, vcc
	v_add_f64 v[8:9], v[8:9], v[10:11]
	v_add_f64 v[12:13], v[20:21], v[8:9]
	v_cvt_i32_f64_e32 v1, v[12:13]
	v_cvt_f64_i32_e32 v[12:13], v1
	v_add_f64 v[8:9], v[8:9], -v[12:13]
	v_add_f64 v[12:13], v[20:21], v[8:9]
	v_cmp_le_f64_e32 vcc, 0.5, v[12:13]
	v_add_f64 v[14:15], v[32:33], -v[14:15]
	v_add_f64 v[8:9], v[12:13], -v[8:9]
	v_addc_co_u32_e64 v56, s[4:5], 0, v1, vcc
	v_mov_b32_e32 v1, 0x3ff00000
	v_add_f64 v[2:3], v[14:15], v[2:3]
	v_add_f64 v[8:9], v[20:21], -v[8:9]
	v_cndmask_b32_e32 v11, 0, v1, vcc
	v_add_f64 v[2:3], v[2:3], v[8:9]
	v_add_f64 v[8:9], v[12:13], -v[10:11]
	v_add_f64 v[10:11], v[8:9], v[2:3]
	s_mov_b32 s0, 0x54442d18
	v_add_f64 v[8:9], v[10:11], -v[8:9]
	s_mov_b32 s1, 0x3ff921fb
	v_add_f64 v[2:3], v[2:3], -v[8:9]
	v_mul_f64 v[8:9], v[10:11], s[0:1]
	s_mov_b32 s4, 0x33145c07
	v_fma_f64 v[14:15], v[10:11], s[0:1], -v[8:9]
	s_mov_b32 s5, 0x3c91a626
	v_fmac_f64_e32 v[14:15], s[4:5], v[10:11]
	v_fmac_f64_e32 v[14:15], s[0:1], v[2:3]
	v_add_f64 v[12:13], v[8:9], v[14:15]
	v_add_f64 v[2:3], v[12:13], -v[8:9]
	v_add_f64 v[14:15], v[14:15], -v[2:3]

.LBB0_327:
	s_bitcmp1_b32 s2, 3
	s_cbranch_scc0 .Lp3_done
	s_mov_b32 s99, 0
	s_waitcnt vmcnt(0) lgkmcnt(0)
	s_barrier
	s_branch .Lp0_body
.Lp3_ret:
	v_and_b32_e32 v1, 15, v0
